# v47 + P2 compressed-KV hand-off: one arrival atomic (+8) per workgroup after a workgroup barrier instead of one per wave
# speedup vs baseline: 1.0204x; 1.0004x over previous
; #define LAS __attribute__((address_space(3)))
; __device__ __forceinline__ unsigned pk2(float lo, float hi) { return f2bf(lo) | (f2bf(hi) << 16); }
; __device__ __forceinline__ void kc_slice(const Prm& P, Ctx& C, const LAS float* wl, int b, int p) {
;     ...
;     unsigned long long* dst = (unsigned long long*)((bf16_t*)(P.ws + WS_KC) + ((size_t)b * 512 + n) * 256) + lane;
;     unsigned long long o = 0ull;
;     if (n < 511) {
;         const f32x4* src = (const f32x4*)(P.out + O_KC + ((size_t)b * SEQ + 16 * n) * 256) + lane;
;         f32x4 v[32];
; #pragma unroll
;         for (int j = 0; j < 32; ++j) v[j] = src[64 * j];
;         f32x4 s = (f32x4){0.f, 0.f, 0.f, 0.f};
; #pragma unroll
;         for (int j = 0; j < 32; ++j) s += v[j] * *(const LAS f32x4*)(wl + j * 256 + 4 * lane);
;         o = ((unsigned long long)pk2(s[2], s[3]) << 32) | pk2(s[0], s[1]);
;     }
;     __hip_atomic_store(dst, o, __ATOMIC_RELAXED, __HIP_MEMORY_SCOPE_AGENT);
;     asm volatile("s_waitcnt vmcnt(0)" ::: "memory");
;     if (lane == 0) __hip_atomic_fetch_add((unsigned*)(P.ws + WS_CTL) + CW_KC + 64 * b, 1u, __ATOMIC_RELAXED, __HIP_MEMORY_SCOPE_AGENT);
.LBB0_834:
	s_ashr_i32 s1, s0, 31
	s_lshl_b32 s2, s90, 18
	v_readlane_b32 s3, v251, 0
	s_add_u32 s2, s3, s2
	v_readlane_b32 s3, v250, 58
	s_addc_u32 s3, s3, 0
	s_lshl_b64 s[0:1], s[0:1], 9
	s_add_u32 s0, s2, s0
	s_addc_u32 s1, s3, s1
	v_lshl_add_u64 v[2:3], v[6:7], 3, s[0:1]
	global_store_dwordx2 v[2:3], v[0:1], off sc1
	s_waitcnt vmcnt(0)
	s_barrier
	v_readlane_b32 s2, v250, 57
	v_cmp_eq_u32_e32 vcc, 0, v6
	s_and_saveexec_b64 s[0:1], vcc
	s_cbranch_execz .LBB0_837
	s_cmp_lg_u32 s2, 0
	s_cbranch_scc1 .LBB0_837
	s_lshl_b32 s3, s90, 8
	v_mov_b32_e32 v0, s3
	v_mov_b32_e32 v1, 8
	global_atomic_add v0, v1, s[88:89]
